# GLA chunk loop: next-chunk operand prefetch issued at the top of the iteration instead of just before barrier B1 (more time to land under contention)
# baseline (speedup 1.0000x reference)
; __device__ __forceinline__ void gla_item(const Params& p, unsigned char* sm, int h, int job0, int jobstride, int nchunks, int tok0, int nvalid, const float* s_init, float* s_out, const int TIDX) {
;     ...
;         if (ci + 1 < nchunks) GLA_LOAD(job0 + (ci + 1) * jobstride, t0 + 64);
.LBB0_127:
	s_waitcnt vmcnt(0)
	s_cmp_lt_u32 s91, s45
	s_cselect_b64 s[98:99], -1, 0
	s_cmp_ge_u32 s91, s45
	s_cbranch_scc1 .Lgla_pf_done
	s_ashr_i32 s97, s96, 31
	s_lshl_b64 s[38:39], s[96:97], 14
	s_add_u32 vcc_lo, s0, s38
	s_addc_u32 vcc_hi, s3, s39
	s_add_u32 s74, s40, s38
	s_addc_u32 s75, s41, s39
	s_add_u32 s38, s79, s38
	s_addc_u32 s39, s80, s39
	v_lshl_add_u64 v[76:77], s[38:39], 0, v[2:3]
	v_lshl_add_u64 v[88:89], s[38:39], 0, v[174:175]
	s_lshl_b64 s[38:39], s[96:97], 15
	s_add_u32 s38, s4, s38
	s_addc_u32 s39, s5, s39
	v_lshl_add_u64 v[68:69], vcc, 0, v[2:3]
	v_lshl_add_u64 v[72:73], s[74:75], 0, v[2:3]
	v_lshl_add_u64 v[80:81], vcc, 0, v[174:175]
	v_lshl_add_u64 v[84:85], s[74:75], 0, v[174:175]
	v_lshl_add_u64 v[92:93], s[38:39], 0, v[2:3]
	v_lshl_add_u64 v[96:97], s[38:39], 0, v[174:175]
	v_lshl_add_u64 v[100:101], v[176:177], 1, s[38:39]
	v_lshl_add_u64 v[104:105], v[178:179], 1, s[38:39]
	global_load_dwordx4 v[68:71], v[68:69], off
	s_nop 0
	global_load_dwordx4 v[72:75], v[72:73], off
	s_nop 0
	global_load_dwordx4 v[76:79], v[76:77], off
	s_nop 0
	global_load_dwordx4 v[80:83], v[80:81], off
	s_nop 0
	global_load_dwordx4 v[84:87], v[84:85], off
	s_nop 0
	global_load_dwordx4 v[88:91], v[88:89], off
	s_nop 0
	global_load_dwordx4 v[92:95], v[92:93], off
	s_nop 0
	global_load_dwordx4 v[96:99], v[96:97], off
	s_nop 0
	global_load_dwordx4 v[100:103], v[100:101], off
	s_nop 0
	global_load_dwordx4 v[104:107], v[104:105], off
	v_mov_b32_e32 v111, 0
	v_mov_b32_e32 v110, 0
	v_mov_b32_e32 v109, 0
	v_mov_b32_e32 v108, 0
	s_and_saveexec_b64 s[38:39], s[6:7]
	s_cbranch_execz .LBB0_130
	s_lshl_b64 s[74:75], s[96:97], 9
	v_lshl_add_u64 v[108:109], v[180:181], 0, s[74:75]
	global_load_dwordx4 v[108:111], v[108:109], off

; __device__ __forceinline__ void gla_item(const Params& p, unsigned char* sm, int h, int job0, int jobstride, int nchunks, int tok0, int nvalid, const float* s_init, float* s_out, const int TIDX) {
;     ...
;         {
;             const int ib = w >> 1;
;             bf16x8 Aa[4], Ba[2][4];
; #pragma unroll
;             for (int ks = 0; ks < 4; ++ks) {
;                 Aa[ks] = *(const bf16x8*)(QEl + (16 * ib + r16) * 272 + (32 * ks + 8 * g) * 2);
;                 Ba[0][ks] = *(const bf16x8*)(KEl + (16 * (2 * (w & 1)) + r16) * 272 + (32 * ks + 8 * g) * 2);
;                 Ba[1][ks] = *(const bf16x8*)(KEl + (16 * (2 * (w & 1) + 1) + r16) * 272 + (32 * ks + 8 * g) * 2);
;             }
;             __builtin_amdgcn_sched_barrier(0);
; #pragma unroll
;             for (int jbi = 0; jbi < 2; ++jbi) {
;                 const int jb = 2 * (w & 1) + jbi; f32x4 acc = (f32x4){0.f, 0.f, 0.f, 0.f};
; #pragma unroll
;                 for (int ks = 0; ks < 4; ++ks) acc = MFMA16(Aa[ks], Ba[jbi][ks], acc);
; #pragma unroll
;                 for (int j = 0; j < 4; ++j) { const int i = 16 * ib + 4 * g + j, jj = 16 * jb + r16; const float v = jj <= i ? acc[j] : 0.f;
;                     *(bf16_t*)(AMl + i * 144 + jj * 2) = (bf16_t)(pk2(v, 0.f) & 0xffffu); }
;             }
;             __builtin_amdgcn_sched_barrier(0);
;         }
;         f32x4 o[4][2];
; #pragma unroll
;         for (int ib = 0; ib < 4; ++ib) { o[ib][0] = (f32x4){0.f, 0.f, 0.f, 0.f}; o[ib][1] = (f32x4){0.f, 0.f, 0.f, 0.f}; }
; #pragma unroll
;         for (int ks = 0; ks < 4; ++ks) {
;             bf16x8 Sf[2];
; #pragma unroll
;             for (int eb = 0; eb < 2; ++eb) {
;                 u32x4 t; t.x = pk2(S[2 * ks][eb][0], S[2 * ks][eb][1]); t.y = pk2(S[2 * ks][eb][2], S[2 * ks][eb][3]);
;                 t.z = pk2(S[2 * ks + 1][eb][0], S[2 * ks + 1][eb][1]); t.w = pk2(S[2 * ks + 1][eb][2], S[2 * ks + 1][eb][3]);
;                 Sf[eb] = __builtin_bit_cast(bf16x8, t);
;             }
;             bf16x8 Aq[4];
; #pragma unroll
;             for (int ib = 0; ib < 4; ++ib) {
;                 const u32x2 a0 = *(const u32x2*)(QEl + (16 * ib + r16) * 272 + (32 * ks + 4 * g) * 2);
;                 const u32x2 a1 = *(const u32x2*)(QEl + (16 * ib + r16) * 272 + (32 * ks + 16 + 4 * g) * 2);
;                 Aq[ib] = __builtin_bit_cast(bf16x8, ((u32x4){a0.x, a0.y, a1.x, a1.y}));
;             }
.Lgla_pf_done:
	ds_read_b128 v[112:115], v224
	ds_read_b128 v[116:119], v224 offset:64
	ds_read_b128 v[120:123], v225 offset:17408
	ds_read_b128 v[124:127], v225 offset:17472
	ds_read_b128 v[128:131], v225 offset:21760
	ds_read_b128 v[132:135], v225 offset:21824
	ds_read_b128 v[136:139], v224 offset:128
	ds_read_b128 v[140:143], v224 offset:192
	ds_read_b128 v[144:147], v225 offset:17536
	ds_read_b128 v[148:151], v225 offset:17600
	ds_read_b128 v[152:155], v225 offset:21888
	ds_read_b128 v[156:159], v225 offset:21952
	s_waitcnt lgkmcnt(0)
	v_mfma_f32_16x16x32_bf16 v[120:123], v[112:115], v[120:123], 0
	v_mfma_f32_16x16x32_bf16 v[112:115], v[112:115], v[128:131], 0
	v_mfma_f32_16x16x32_bf16 v[112:115], v[116:119], v[132:135], v[112:115]
	v_mfma_f32_16x16x32_bf16 v[120:123], v[116:119], v[124:127], v[120:123]
	v_mfma_f32_16x16x32_bf16 v[112:115], v[136:139], v[152:155], v[112:115]
	v_mfma_f32_16x16x32_bf16 v[120:123], v[136:139], v[144:147], v[120:123]
	v_mfma_f32_16x16x32_bf16 v[112:115], v[140:143], v[156:159], v[112:115]
	v_mfma_f32_16x16x32_bf16 v[120:123], v[140:143], v[148:151], v[120:123]
	s_nop 6
	v_cndmask_b32_e64 v112, v112, 0, s[20:21]
	v_cvt_pk_bf16_f32 v112, v112, v1
	ds_write_b16 v227, v112
	v_cndmask_b32_e64 v112, v113, 0, s[22:23]
	v_cvt_pk_bf16_f32 v112, v112, v1
	v_cndmask_b32_e64 v120, v120, 0, s[12:13]
	v_cndmask_b32_e64 v116, v122, 0, s[16:17]
	ds_write_b16 v227, v112 offset:144
	v_cndmask_b32_e64 v112, v114, 0, s[24:25]
	v_cvt_pk_bf16_f32 v120, v120, v1
	v_cvt_pk_bf16_f32 v116, v116, v1
	v_cvt_pk_bf16_f32 v112, v112, v1
	ds_write_b16 v226, v120
	v_cndmask_b32_e64 v120, v121, 0, s[14:15]
	ds_write_b16 v226, v116 offset:288
	v_cndmask_b32_e64 v116, v123, 0, s[18:19]
	ds_write_b16 v227, v112 offset:288
	v_cndmask_b32_e64 v112, v115, 0, s[26:27]
	v_cvt_pk_bf16_f32 v120, v120, v1
	ds_write_b16 v226, v120 offset:144
	v_cvt_pk_bf16_f32 v116, v116, v1
	ds_write_b16 v226, v116 offset:432
	v_cvt_pk_bf16_f32 v112, v112, v1
	ds_write_b16 v227, v112 offset:432
	v_add_u32_e32 v237, 0x1000, v228
	v_add_u32_e32 v238, 0x2000, v228
	v_add_u32_e32 v239, 0x3000, v228
	ds_read2_b64 v[116:119], v228 offset1:4
	ds_read2_b64 v[120:123], v237 offset0:32 offset1:36
	ds_read2_b64 v[124:127], v238 offset0:64 offset1:68
	ds_read2_b64 v[128:131], v239 offset0:96 offset1:100
	v_cvt_pk_bf16_f32 v112, v4, v5
	v_cvt_pk_bf16_f32 v113, v6, v7
	v_cvt_pk_bf16_f32 v114, v12, v13
	v_cvt_pk_bf16_f32 v115, v14, v15
	v_cvt_pk_bf16_f32 v132, v8, v9
	v_cvt_pk_bf16_f32 v133, v10, v11
	v_cvt_pk_bf16_f32 v134, v16, v17
	v_cvt_pk_bf16_f32 v135, v18, v19
	s_waitcnt lgkmcnt(3)
	v_mfma_f32_16x16x32_bf16 v[136:139], v[116:119], v[112:115], 0
	v_mfma_f32_16x16x32_bf16 v[116:119], v[116:119], v[132:135], 0
	s_waitcnt lgkmcnt(2)
	v_mfma_f32_16x16x32_bf16 v[140:143], v[120:123], v[112:115], 0
	v_mfma_f32_16x16x32_bf16 v[120:123], v[120:123], v[132:135], 0
	s_waitcnt lgkmcnt(1)
	v_mfma_f32_16x16x32_bf16 v[144:147], v[124:127], v[112:115], 0
	v_mfma_f32_16x16x32_bf16 v[124:127], v[124:127], v[132:135], 0
	s_waitcnt lgkmcnt(0)
	v_mfma_f32_16x16x32_bf16 v[112:115], v[128:131], v[112:115], 0
	v_mfma_f32_16x16x32_bf16 v[128:131], v[128:131], v[132:135], 0
	ds_read2_b64 v[148:151], v228 offset0:8 offset1:12
	ds_read2_b64 v[152:155], v237 offset0:40 offset1:44
	ds_read2_b64 v[156:159], v238 offset0:72 offset1:76
	ds_read2_b64 v[160:163], v239 offset0:104 offset1:108
	v_cvt_pk_bf16_f32 v132, v20, v21
	v_cvt_pk_bf16_f32 v133, v22, v23
	v_cvt_pk_bf16_f32 v134, v28, v29
	v_cvt_pk_bf16_f32 v135, v30, v31
	v_cvt_pk_bf16_f32 v164, v24, v25
	v_cvt_pk_bf16_f32 v165, v26, v27
	v_cvt_pk_bf16_f32 v166, v32, v33
	v_cvt_pk_bf16_f32 v167, v34, v35
	s_waitcnt lgkmcnt(3)
	v_mfma_f32_16x16x32_bf16 v[136:139], v[148:151], v[132:135], v[136:139]
	v_mfma_f32_16x16x32_bf16 v[116:119], v[148:151], v[164:167], v[116:119]
	s_waitcnt lgkmcnt(2)
	v_mfma_f32_16x16x32_bf16 v[140:143], v[152:155], v[132:135], v[140:143]
	v_mfma_f32_16x16x32_bf16 v[120:123], v[152:155], v[164:167], v[120:123]
	s_waitcnt lgkmcnt(1)
	v_mfma_f32_16x16x32_bf16 v[144:147], v[156:159], v[132:135], v[144:147]
	v_mfma_f32_16x16x32_bf16 v[124:127], v[156:159], v[164:167], v[124:127]
	s_waitcnt lgkmcnt(0)
	v_mfma_f32_16x16x32_bf16 v[112:115], v[160:163], v[132:135], v[112:115]
	v_mfma_f32_16x16x32_bf16 v[128:131], v[160:163], v[164:167], v[128:131]
	ds_read2_b64 v[148:151], v228 offset0:16 offset1:20
	ds_read2_b64 v[152:155], v237 offset0:48 offset1:52
	ds_read2_b64 v[156:159], v238 offset0:80 offset1:84
	ds_read2_b64 v[160:163], v239 offset0:112 offset1:116
	v_cvt_pk_bf16_f32 v132, v36, v37
	v_cvt_pk_bf16_f32 v133, v38, v39
	v_cvt_pk_bf16_f32 v134, v44, v45
	v_cvt_pk_bf16_f32 v135, v46, v47
	v_cvt_pk_bf16_f32 v164, v40, v41
	v_cvt_pk_bf16_f32 v165, v42, v43
	v_cvt_pk_bf16_f32 v166, v48, v49
	v_cvt_pk_bf16_f32 v167, v50, v51
	s_waitcnt lgkmcnt(3)
	v_mfma_f32_16x16x32_bf16 v[136:139], v[148:151], v[132:135], v[136:139]
	v_mfma_f32_16x16x32_bf16 v[116:119], v[148:151], v[164:167], v[116:119]
	s_waitcnt lgkmcnt(2)
	v_mfma_f32_16x16x32_bf16 v[140:143], v[152:155], v[132:135], v[140:143]
	v_mfma_f32_16x16x32_bf16 v[120:123], v[152:155], v[164:167], v[120:123]
	s_waitcnt lgkmcnt(1)
	v_mfma_f32_16x16x32_bf16 v[124:127], v[156:159], v[164:167], v[124:127]
	s_waitcnt lgkmcnt(0)
	v_mfma_f32_16x16x32_bf16 v[112:115], v[160:163], v[132:135], v[112:115]
	v_mfma_f32_16x16x32_bf16 v[128:131], v[160:163], v[164:167], v[128:131]
	v_mfma_f32_16x16x32_bf16 v[152:155], v[156:159], v[132:135], v[144:147]
	ds_read2_b64 v[148:151], v228 offset0:24 offset1:28
	ds_read2_b64 v[156:159], v237 offset0:56 offset1:60
	ds_read2_b64 v[160:163], v238 offset0:88 offset1:92
	ds_read2_b64 v[164:167], v239 offset0:120 offset1:124
	v_cvt_pk_bf16_f32 v132, v52, v53
	v_cvt_pk_bf16_f32 v133, v54, v55
	v_cvt_pk_bf16_f32 v134, v60, v61
	v_cvt_pk_bf16_f32 v135, v62, v63
	v_cvt_pk_bf16_f32 v238, v56, v57
	v_cvt_pk_bf16_f32 v239, v58, v59
	v_cvt_pk_bf16_f32 v240, v64, v65
	v_cvt_pk_bf16_f32 v241, v66, v67
	s_waitcnt lgkmcnt(3)
; #define MFMA16(a, b, c) __builtin_amdgcn_mfma_f32_16x16x32_bf16((a), (b), (c), 0, 0, 0)
; __device__ __forceinline__ void gla_item(const Params& p, unsigned char* sm, int h, int job0, int jobstride, int nchunks, int tok0, int nvalid, const float* s_init, float* s_out, const int TIDX) {
;     ...
;         bf16x8 Vf[2][2];
; #pragma unroll
;         for (int ks = 0; ks < 2; ++ks)
; #pragma unroll
;             for (int eb = 0; eb < 2; ++eb) Vf[ks][eb] = *(const bf16x8*)(VTl + (32 * w + 16 * eb + r16) * 144 + (32 * ks + 8 * g) * 2);
; #pragma unroll
;         for (int dp = 0; dp < 4; ++dp) {
;             bf16x8 Ak[2][2]; f32x4 e4[2];
; #pragma unroll
;             for (int q = 0; q < 2; ++q) { const int db = 2 * dp + q; e4[q] = *(const f32x4*)(EBl + 16 * db + 4 * g);
; #pragma unroll
;                 for (int ks = 0; ks < 2; ++ks) Ak[q][ks] = *(const bf16x8*)(KLl + (16 * db + r16) * 144 + (32 * ks + 8 * g) * 2); }
;             __builtin_amdgcn_sched_barrier(0);
; #pragma unroll
;             for (int q = 0; q < 2; ++q) { const int db = 2 * dp + q;
;                 S[db][0] = S[db][0] * e4[q]; S[db][1] = S[db][1] * e4[q];
; #pragma unroll
;                 for (int ks = 0; ks < 2; ++ks) { S[db][0] = MFMA16(Ak[q][ks], Vf[ks][0], S[db][0]); S[db][1] = MFMA16(Ak[q][ks], Vf[ks][1], S[db][1]); } }
;             __builtin_amdgcn_sched_barrier(0);
;         }
;         __builtin_amdgcn_sched_barrier(0);
;         if (ci + 1 < nchunks) GLA_LOAD(job0 + (ci + 1) * jobstride, t0 + 64);
	v_mfma_f32_16x16x32_bf16 v[144:147], v[148:151], v[132:135], v[136:139]
	v_mfma_f32_16x16x32_bf16 v[148:151], v[148:151], v[238:241], v[116:119]
	s_waitcnt lgkmcnt(2)
	v_mfma_f32_16x16x32_bf16 v[136:139], v[156:159], v[132:135], v[140:143]
	v_mfma_f32_16x16x32_bf16 v[140:143], v[156:159], v[238:241], v[120:123]
	s_waitcnt lgkmcnt(1)
	v_mfma_f32_16x16x32_bf16 v[120:123], v[160:163], v[132:135], v[152:155]
	v_mfma_f32_16x16x32_bf16 v[124:127], v[160:163], v[238:241], v[124:127]
	s_waitcnt lgkmcnt(0)
	v_mfma_f32_16x16x32_bf16 v[112:115], v[164:167], v[132:135], v[112:115]
	v_mfma_f32_16x16x32_bf16 v[116:119], v[164:167], v[238:241], v[128:131]
	v_add_u32_e32 v152, 0, v209
	v_add_u32_e32 v195, v210, v0
	s_nop 0
	ds_read_b128 v[128:131], v229 offset:53248
	ds_read_b128 v[132:135], v229 offset:53312
	ds_read_b128 v[164:167], v229 offset:55552
	ds_read_b128 v[160:163], v229 offset:55616
	v_add_u32_e32 v237, 0x18400, v152
	ds_read_b128 v[152:155], v195 offset:34816
	ds_read_b128 v[156:159], v195 offset:34880
	ds_read_b128 v[238:241], v237
	ds_read_b128 v[242:245], v237 offset:64
	ds_read_b128 v[246:249], v195 offset:37120
	ds_read_b128 v[250:253], v195 offset:37184
	s_waitcnt lgkmcnt(3)
	v_pk_mul_f32 v[6:7], v[6:7], v[240:241]
	v_pk_mul_f32 v[4:5], v[4:5], v[238:239]
	v_pk_mul_f32 v[10:11], v[10:11], v[240:241]
	v_pk_mul_f32 v[8:9], v[8:9], v[238:239]
	s_waitcnt lgkmcnt(2)
	v_pk_mul_f32 v[14:15], v[14:15], v[244:245]
	v_pk_mul_f32 v[12:13], v[12:13], v[242:243]
	v_pk_mul_f32 v[18:19], v[18:19], v[244:245]
	v_pk_mul_f32 v[16:17], v[16:17], v[242:243]
	v_mfma_f32_16x16x32_bf16 v[4:7], v[152:155], v[128:131], v[4:7]
	v_mfma_f32_16x16x32_bf16 v[8:11], v[152:155], v[164:167], v[8:11]
	s_waitcnt lgkmcnt(1)
	v_mfma_f32_16x16x32_bf16 v[12:15], v[246:249], v[128:131], v[12:15]
	v_mfma_f32_16x16x32_bf16 v[16:19], v[246:249], v[164:167], v[16:19]
	v_mfma_f32_16x16x32_bf16 v[4:7], v[156:159], v[132:135], v[4:7]
	v_mfma_f32_16x16x32_bf16 v[8:11], v[156:159], v[160:163], v[8:11]
	s_waitcnt lgkmcnt(0)
	v_mfma_f32_16x16x32_bf16 v[12:15], v[250:253], v[132:135], v[12:15]
	v_mfma_f32_16x16x32_bf16 v[16:19], v[250:253], v[160:163], v[16:19]
	ds_read_b128 v[152:155], v195 offset:39424
	ds_read_b128 v[156:159], v195 offset:39488
	ds_read_b128 v[238:241], v237 offset:128
	ds_read_b128 v[242:245], v237 offset:192
	ds_read_b128 v[246:249], v195 offset:41728
	ds_read_b128 v[250:253], v195 offset:41792
	s_waitcnt lgkmcnt(3)
	v_pk_mul_f32 v[22:23], v[22:23], v[240:241]
	v_pk_mul_f32 v[20:21], v[20:21], v[238:239]
	v_pk_mul_f32 v[26:27], v[26:27], v[240:241]
	v_pk_mul_f32 v[24:25], v[24:25], v[238:239]
	s_waitcnt lgkmcnt(2)
	v_pk_mul_f32 v[30:31], v[30:31], v[244:245]
	v_pk_mul_f32 v[28:29], v[28:29], v[242:243]
	v_pk_mul_f32 v[34:35], v[34:35], v[244:245]
	v_pk_mul_f32 v[32:33], v[32:33], v[242:243]
	v_mfma_f32_16x16x32_bf16 v[20:23], v[152:155], v[128:131], v[20:23]
	v_mfma_f32_16x16x32_bf16 v[24:27], v[152:155], v[164:167], v[24:27]
	s_waitcnt lgkmcnt(1)
	v_mfma_f32_16x16x32_bf16 v[28:31], v[246:249], v[128:131], v[28:31]
	v_mfma_f32_16x16x32_bf16 v[32:35], v[246:249], v[164:167], v[32:35]
	v_mfma_f32_16x16x32_bf16 v[20:23], v[156:159], v[132:135], v[20:23]
	v_mfma_f32_16x16x32_bf16 v[24:27], v[156:159], v[160:163], v[24:27]
	s_waitcnt lgkmcnt(0)
	v_mfma_f32_16x16x32_bf16 v[28:31], v[250:253], v[132:135], v[28:31]
	v_mfma_f32_16x16x32_bf16 v[32:35], v[250:253], v[160:163], v[32:35]
	ds_read_b128 v[152:155], v195 offset:44032
	ds_read_b128 v[156:159], v195 offset:44096
	ds_read_b128 v[238:241], v237 offset:256
	ds_read_b128 v[242:245], v237 offset:320
	ds_read_b128 v[246:249], v195 offset:46336
	ds_read_b128 v[250:253], v195 offset:46400
	s_waitcnt lgkmcnt(3)
	v_pk_mul_f32 v[38:39], v[38:39], v[240:241]
	v_pk_mul_f32 v[36:37], v[36:37], v[238:239]
	v_pk_mul_f32 v[42:43], v[42:43], v[240:241]
	v_pk_mul_f32 v[40:41], v[40:41], v[238:239]
	s_waitcnt lgkmcnt(2)
	v_pk_mul_f32 v[46:47], v[46:47], v[244:245]
	v_pk_mul_f32 v[44:45], v[44:45], v[242:243]
	v_pk_mul_f32 v[50:51], v[50:51], v[244:245]
	v_pk_mul_f32 v[48:49], v[48:49], v[242:243]
	v_mfma_f32_16x16x32_bf16 v[36:39], v[152:155], v[128:131], v[36:39]
	v_mfma_f32_16x16x32_bf16 v[40:43], v[152:155], v[164:167], v[40:43]
	s_waitcnt lgkmcnt(1)
	v_mfma_f32_16x16x32_bf16 v[44:47], v[246:249], v[128:131], v[44:47]
	v_mfma_f32_16x16x32_bf16 v[48:51], v[246:249], v[164:167], v[48:51]
	v_mfma_f32_16x16x32_bf16 v[36:39], v[156:159], v[132:135], v[36:39]
	v_mfma_f32_16x16x32_bf16 v[40:43], v[156:159], v[160:163], v[40:43]
	s_waitcnt lgkmcnt(0)
	v_mfma_f32_16x16x32_bf16 v[44:47], v[250:253], v[132:135], v[44:47]
	v_mfma_f32_16x16x32_bf16 v[48:51], v[250:253], v[160:163], v[48:51]
	ds_read_b128 v[152:155], v195 offset:48640
	ds_read_b128 v[156:159], v195 offset:48704
	ds_read_b128 v[238:241], v237 offset:384
	ds_read_b128 v[242:245], v237 offset:448
	ds_read_b128 v[246:249], v195 offset:50944
	ds_read_b128 v[250:253], v195 offset:51008
	s_waitcnt lgkmcnt(3)
	v_pk_mul_f32 v[54:55], v[54:55], v[240:241]
	v_pk_mul_f32 v[52:53], v[52:53], v[238:239]
	v_pk_mul_f32 v[58:59], v[58:59], v[240:241]
	v_pk_mul_f32 v[56:57], v[56:57], v[238:239]
	s_waitcnt lgkmcnt(2)
	v_pk_mul_f32 v[62:63], v[62:63], v[244:245]
	v_pk_mul_f32 v[60:61], v[60:61], v[242:243]
	v_pk_mul_f32 v[66:67], v[66:67], v[244:245]
	v_pk_mul_f32 v[64:65], v[64:65], v[242:243]
	v_mfma_f32_16x16x32_bf16 v[52:55], v[152:155], v[128:131], v[52:55]
	v_mfma_f32_16x16x32_bf16 v[56:59], v[152:155], v[164:167], v[56:59]
	s_waitcnt lgkmcnt(1)
	v_mfma_f32_16x16x32_bf16 v[60:63], v[246:249], v[128:131], v[60:63]
	v_mfma_f32_16x16x32_bf16 v[64:67], v[246:249], v[164:167], v[64:67]
	v_mfma_f32_16x16x32_bf16 v[52:55], v[156:159], v[132:135], v[52:55]
	v_mfma_f32_16x16x32_bf16 v[56:59], v[156:159], v[160:163], v[56:59]
	s_waitcnt lgkmcnt(0)
	v_mfma_f32_16x16x32_bf16 v[60:63], v[250:253], v[132:135], v[60:63]
	v_mfma_f32_16x16x32_bf16 v[64:67], v[250:253], v[160:163], v[64:67]
